# RG-LRU chunk scan: hipcc's 5-instruction DPP scan steps (init mov + v_mov_dpp + pk_mul/pk_fma) rewritten as in-place fused v_fmac_f32_dpp / v_mul_f32_dpp
# speedup vs baseline: 1.0158x; 1.0098x over previous
; #define LAS __attribute__((address_space(3)))
; __device__ __forceinline__ float bf2f(unsigned short v) { return __uint_as_float((unsigned)v << 16); }
; __device__ __forceinline__ void rec_et(LAS unsigned char* lds, const RecArgs& a, const bf16_t* Wr, const bf16_t* Wi, const int et, const int n, const int r32, const int hi, ...
;     ...
;                 for (int kk = 0; kk < 4; ++kk) { const bf16x8 xb = *(const LAS bf16x8*)(lds + (32 * tt + r32) * XC_STRIDE + (64 * n + 16 * kk + 8 * hi) * 2);
;                     const bf16x8 war = *(const bf16x8*)(Wr + (32 * et + r32) * 64 + 16 * kk + 8 * hi), wai = *(const bf16x8*)(Wi + (32 * et + r32) * 64 + 16 * kk + 8 * hi);
;                     accr = __builtin_amdgcn_mfma_f32_32x32x16_bf16(war, xb, accr, 0, 0, 0);
;                     acci = __builtin_amdgcn_mfma_f32_32x32x16_bf16(wai, xb, acci, 0, 0, 0); }
;                 const int tok = 32 * tt + r32, t = t0 + tok; const bool valid = tok < nvalid;
;                 float av[16], uv[16];
; #pragma unroll
;                 for (int r = 0; r < 16; ++r) { const int ch = 64 * n + 32 * et + (r & 3) + 8 * (r >> 2) + 4 * hi;
;                     const float xcv = bf2f(*(const LAS unsigned short*)(lds + tok * XC_STRIDE + ch * 2));
;                     const float rg = __builtin_amdgcn_rcpf(1.0f + __expf(-(accr[r] + Pbrg[ch]))), ig = __builtin_amdgcn_rcpf(1.0f + __expf(-(acci[r] + Pbig[ch])));
;                     const float la = rg * Plsl[ch]; float aa = __expf(la); float mult = __builtin_amdgcn_sqrtf(fmaxf(__builtin_fmaf(-aa, aa, 1.0f), 0.f)); if (t == 0) mult = 1.0f;
;                     float uu = mult * ig * xcv; if (!valid) { aa = 1.0f; uu = 0.f; }
;                     av[r] = aa; uv[r] = uu; }
.LBB0_473:
	global_load_dwordx4 v[2:5], v[90:91], off
	global_load_dwordx4 v[6:9], v[92:93], off
	global_load_dwordx4 v[82:85], v[90:91], off offset:32
	ds_read_b128 v[10:13], v248
	ds_read_b128 v[86:89], v248 offset:32
	global_load_dwordx4 v[172:175], v[92:93], off offset:32
	global_load_dwordx4 v[176:179], v[90:91], off offset:64
	v_cmp_eq_u32_e32 vcc, s21, v250
	v_cmp_gt_u32_e64 s[38:39], s14, v250
	s_cmp_eq_u32 s27, 0
	s_waitcnt vmcnt(4) lgkmcnt(1)
	v_mfma_f32_32x32x16_bf16 v[18:33], v[2:5], v[10:13], 0
	s_waitcnt vmcnt(3)
	v_mfma_f32_32x32x16_bf16 v[2:17], v[6:9], v[10:13], 0
	s_waitcnt vmcnt(2) lgkmcnt(0)
	v_mfma_f32_32x32x16_bf16 v[18:33], v[82:85], v[86:89], v[18:33]
	global_load_dwordx4 v[82:85], v[92:93], off offset:64
	s_waitcnt vmcnt(2)
	v_mfma_f32_32x32x16_bf16 v[2:17], v[172:175], v[86:89], v[2:17]
	global_load_dwordx4 v[86:89], v[90:91], off offset:96
	ds_read_b128 v[172:175], v248 offset:64
	ds_read_b128 v[180:183], v248 offset:96
	s_waitcnt vmcnt(2) lgkmcnt(1)
	v_mfma_f32_32x32x16_bf16 v[18:33], v[176:179], v[172:175], v[18:33]
	global_load_dwordx4 v[176:179], v[92:93], off offset:96
	s_waitcnt vmcnt(2)
	v_mfma_f32_32x32x16_bf16 v[2:17], v[82:85], v[172:175], v[2:17]
	s_waitcnt vmcnt(1) lgkmcnt(0)
	v_mfma_f32_32x32x16_bf16 v[18:33], v[86:89], v[180:183], v[18:33]
	ds_read2_b64 v[86:89], v249 offset1:2
	ds_read2_b64 v[82:85], v249 offset0:4 offset1:6
	s_waitcnt vmcnt(0)
	v_mfma_f32_32x32x16_bf16 v[2:17], v[176:179], v[180:183], v[2:17]
	s_nop 7
	v_add_f32_e32 v0, v18, v34
	v_add_f32_e32 v18, v19, v35
	v_mul_f32_e32 v0, 0xbfb8aa3b, v0
	v_mul_f32_e32 v18, 0xbfb8aa3b, v18
	v_exp_f32_e32 v0, v0
	v_exp_f32_e32 v18, v18
	v_add_f32_e32 v19, v20, v36
	v_add_f32_e32 v2, v2, v38
	v_mul_f32_e32 v2, 0xbfb8aa3b, v2
	v_exp_f32_e32 v2, v2
	v_add_f32_e32 v4, v4, v40
	v_add_f32_e32 v20, v21, v37
	v_add_f32_e32 v21, v22, v46
	v_add_f32_e32 v6, v6, v50
	v_add_f32_e32 v22, v23, v47
	v_add_f32_e32 v23, v24, v48
	v_add_f32_e32 v24, v25, v49
	v_add_f32_e32 v0, 1.0, v0
	v_add_f32_e32 v5, v5, v41
	v_add_f32_e32 v7, v7, v51
	v_mul_f32_e32 v4, 0xbfb8aa3b, v4
	v_mul_f32_e32 v20, 0xbfb8aa3b, v20
	v_mul_f32_e32 v6, 0xbfb8aa3b, v6
	v_mul_f32_e32 v22, 0xbfb8aa3b, v22
	v_mul_f32_e32 v24, 0xbfb8aa3b, v24
	v_add_f32_e32 v2, 1.0, v2
	v_add_f32_e32 v18, 1.0, v18
	v_rcp_f32_e32 v0, v0
	v_mul_f32_e32 v5, 0xbfb8aa3b, v5
	v_mul_f32_e32 v21, 0xbfb8aa3b, v21
	v_mul_f32_e32 v7, 0xbfb8aa3b, v7
	v_mul_f32_e32 v23, 0xbfb8aa3b, v23
	v_exp_f32_e32 v4, v4
	v_exp_f32_e32 v20, v20
	v_exp_f32_e32 v6, v6
	v_exp_f32_e32 v22, v22
	v_exp_f32_e32 v172, v24
	v_rcp_f32_e32 v24, v2
	v_rcp_f32_e32 v2, v18
	v_exp_f32_e32 v5, v5
	v_exp_f32_e32 v21, v21
	v_exp_f32_e32 v7, v7
	v_exp_f32_e32 v23, v23
	v_add_f32_e32 v3, v3, v39
	v_mul_f32_e32 v0, v42, v0
	v_mul_f32_e32 v3, 0xbfb8aa3b, v3
	v_mul_f32_e32 v19, 0xbfb8aa3b, v19
	v_add_f32_e32 v4, 1.0, v4
	v_add_f32_e32 v20, 1.0, v20
	v_add_f32_e32 v6, 1.0, v6
	v_add_f32_e32 v173, 1.0, v22
	v_mul_f32_e32 v2, v43, v2
	v_mul_f32_e32 v0, 0x3fb8aa3b, v0
	v_exp_f32_e32 v3, v3
	v_exp_f32_e32 v19, v19
	v_add_f32_e32 v5, 1.0, v5
	v_add_f32_e32 v21, 1.0, v21
	v_add_f32_e32 v7, 1.0, v7
	v_add_f32_e32 v174, 1.0, v23
	v_rcp_f32_e32 v22, v4
	v_rcp_f32_e32 v4, v20
	v_rcp_f32_e32 v20, v6
	v_rcp_f32_e32 v6, v173
	v_mul_f32_e32 v2, 0x3fb8aa3b, v2
	v_exp_f32_e32 v173, v0
	v_rcp_f32_e32 v23, v5
	v_rcp_f32_e32 v5, v21
	v_rcp_f32_e32 v21, v7
	v_rcp_f32_e32 v7, v174
	v_exp_f32_e32 v174, v2
	v_add_f32_e32 v3, 1.0, v3
	v_add_f32_e32 v19, 1.0, v19
	v_fma_f32 v0, -v173, v173, 1.0
	v_rcp_f32_e32 v25, v3
	v_rcp_f32_e32 v3, v19
	v_fma_f32 v2, -v174, v174, 1.0
	v_max_f32_e32 v0, 0, v0
	v_max_f32_e32 v2, 0, v2
	v_sqrt_f32_e32 v180, v0
	v_add_f32_e32 v0, 1.0, v172
	v_sqrt_f32_e32 v181, v2
	v_rcp_f32_e32 v0, v0
	v_add_f32_e32 v2, v9, v53
	v_mul_f32_e32 v2, 0xbfb8aa3b, v2
	v_mul_f32_e32 v3, v44, v3
	v_exp_f32_e32 v2, v2
	v_mul_f32_e32 v3, 0x3fb8aa3b, v3
	v_exp_f32_e32 v182, v3
	v_mul_f32_e32 v0, v57, v0
	v_mul_f32_e32 v0, 0x3fb8aa3b, v0
	v_exp_f32_e32 v200, v0
	v_add_f32_e32 v0, 1.0, v2
	v_add_f32_e32 v2, v26, v58
	v_mul_f32_e32 v2, 0xbfb8aa3b, v2
	v_fma_f32 v3, -v182, v182, 1.0
	v_exp_f32_e32 v2, v2
	v_max_f32_e32 v3, 0, v3
	v_add_f32_e32 v8, v8, v52
	v_sqrt_f32_e32 v191, v3
	v_add_f32_e32 v3, v10, v62
	v_mul_f32_e32 v8, 0xbfb8aa3b, v8
	v_mul_f32_e32 v3, 0xbfb8aa3b, v3
	v_exp_f32_e32 v8, v8
	v_exp_f32_e32 v3, v3
	v_add_f32_e32 v2, 1.0, v2
	v_rcp_f32_e32 v2, v2
	v_rcp_f32_e32 v19, v0
	v_fma_f32 v0, -v200, v200, 1.0
	v_max_f32_e32 v0, 0, v0
	v_add_f32_e32 v8, 1.0, v8
	v_sqrt_f32_e32 v202, v0
	v_add_f32_e32 v0, 1.0, v3
	v_rcp_f32_e32 v18, v8
	v_rcp_f32_e32 v8, v0
	v_mul_f32_e32 v0, v66, v2
	v_mul_f32_e32 v0, 0x3fb8aa3b, v0
	v_exp_f32_e32 v184, v0
	v_add_f32_e32 v0, v27, v59
	v_mul_f32_e32 v0, 0xbfb8aa3b, v0
	v_exp_f32_e32 v0, v0
	v_fma_f32 v2, -v184, v184, 1.0
	v_max_f32_e32 v2, 0, v2
	v_sqrt_f32_e32 v186, v2
	v_add_f32_e32 v0, 1.0, v0
	v_rcp_f32_e32 v0, v0
	v_add_f32_e32 v2, v11, v63
	v_mul_f32_e32 v2, 0xbfb8aa3b, v2
	v_mul_f32_e32 v6, v55, v6
	v_mul_f32_e32 v0, v67, v0
	v_mul_f32_e32 v0, 0x3fb8aa3b, v0
	v_exp_f32_e32 v203, v0
	v_add_f32_e32 v0, v28, v60
	v_mul_f32_e32 v0, 0xbfb8aa3b, v0
	v_exp_f32_e32 v0, v0
	v_exp_f32_e32 v2, v2
	v_mul_f32_e32 v6, 0x3fb8aa3b, v6
	v_add_f32_e32 v3, v12, v64
	v_add_f32_e32 v0, 1.0, v0
	v_rcp_f32_e32 v0, v0
	v_exp_f32_e32 v189, v6
	v_mul_f32_e32 v3, 0xbfb8aa3b, v3
	v_exp_f32_e32 v3, v3
	v_mul_f32_e32 v0, v68, v0
	v_mul_f32_e32 v0, 0x3fb8aa3b, v0
	v_exp_f32_e32 v188, v0
	v_add_f32_e32 v0, v29, v61
	v_mul_f32_e32 v0, 0xbfb8aa3b, v0
	v_exp_f32_e32 v0, v0
	v_add_f32_e32 v2, 1.0, v2
	v_rcp_f32_e32 v9, v2
	v_fma_f32 v2, -v203, v203, 1.0
; #define SCAN_STEP(CTRL, RM) do { _Pragma("unroll") for (int r = 0; r < 16; ++r) { const float ap = DPP_F(1.0f, av[r], CTRL, RM), up = DPP_F(0.0f, uv[r], CTRL, RM); uv[r] = __builtin_fmaf(av[r], up, uv[r]); av[r] = av[r] * ap; } } while (0)
; __device__ __forceinline__ void rec_et(LAS unsigned char* lds, const RecArgs& a, const bf16_t* Wr, const bf16_t* Wi, const int et, const int n, const int r32, const int hi, ...
;     ...
;                 SCAN_STEP(0x111, 0xf); SCAN_STEP(0x112, 0xf); SCAN_STEP(0x114, 0xf); SCAN_STEP(0x118, 0xf);
;                 SCAN_STEP(0x142, 0xa);
	v_fma_f32 v6, -v189, v189, 1.0
	v_max_f32_e32 v2, 0, v2
	v_max_f32_e32 v6, 0, v6
	v_sqrt_f32_e32 v187, v2
	v_add_f32_e32 v2, 1.0, v3
	v_add_f32_e32 v0, 1.0, v0
	v_sqrt_f32_e32 v199, v6
	v_rcp_f32_e32 v6, v2
	v_fma_f32 v2, -v188, v188, 1.0
	v_rcp_f32_e32 v0, v0
	v_add_f32_e32 v3, v13, v65
	v_max_f32_e32 v2, 0, v2
	v_mul_f32_e32 v3, 0xbfb8aa3b, v3
	v_mul_f32_e32 v7, v56, v7
	v_exp_f32_e32 v3, v3
	v_sqrt_f32_e32 v27, v2
	v_add_f32_e32 v2, v30, v70
	v_mul_f32_e32 v7, 0x3fb8aa3b, v7
	v_mul_f32_e32 v2, 0xbfb8aa3b, v2
	v_exp_f32_e32 v190, v7
	v_mul_f32_e32 v0, v69, v0
	v_exp_f32_e32 v2, v2
	v_mul_f32_e32 v4, v45, v4
	v_mul_f32_e32 v0, 0x3fb8aa3b, v0
	v_mul_f32_e32 v4, 0x3fb8aa3b, v4
	v_exp_f32_e32 v29, v0
	v_add_f32_e32 v0, 1.0, v3
	v_add_f32_e32 v3, v14, v74
	v_exp_f32_e32 v183, v4
	v_mul_f32_e32 v3, 0xbfb8aa3b, v3
	v_fma_f32 v7, -v190, v190, 1.0
	v_exp_f32_e32 v3, v3
	v_add_f32_e32 v2, 1.0, v2
	v_max_f32_e32 v7, 0, v7
	v_rcp_f32_e32 v2, v2
	v_sqrt_f32_e32 v201, v7
	v_rcp_f32_e32 v7, v0
	v_fma_f32 v0, -v29, v29, 1.0
	v_fma_f32 v4, -v183, v183, 1.0
	v_max_f32_e32 v0, 0, v0
	v_max_f32_e32 v4, 0, v4
	v_sqrt_f32_e32 v28, v0
	v_add_f32_e32 v0, 1.0, v3
	v_sqrt_f32_e32 v193, v4
	v_rcp_f32_e32 v4, v0
	v_mul_f32_e32 v0, v78, v2
	v_mul_f32_e32 v0, 0x3fb8aa3b, v0
	v_exp_f32_e32 v26, v0
	v_add_f32_e32 v0, v31, v71
	v_mul_f32_e32 v0, 0xbfb8aa3b, v0
	v_exp_f32_e32 v0, v0
	v_fma_f32 v2, -v26, v26, 1.0
	v_max_f32_e32 v2, 0, v2
	v_sqrt_f32_e32 v12, v2
	v_add_f32_e32 v0, 1.0, v0
	v_rcp_f32_e32 v0, v0
	v_add_f32_e32 v2, v15, v75
	v_cndmask_b32_e64 v181, v181, 1.0, vcc
	v_cndmask_b32_e64 v180, v180, 1.0, vcc
	v_mul_f32_e32 v0, v79, v0
	v_mul_f32_e32 v0, 0x3fb8aa3b, v0
	v_exp_f32_e32 v15, v0
	v_add_f32_e32 v0, v32, v72
	v_mul_f32_e32 v0, 0xbfb8aa3b, v0
	v_exp_f32_e32 v0, v0
	s_waitcnt lgkmcnt(1)
	v_and_b32_e32 v179, 0xffff0000, v86
	v_lshlrev_b32_e32 v178, 16, v86
	v_pk_mul_f32 v[24:25], v[24:25], v[180:181]
	v_add_f32_e32 v0, 1.0, v0
	v_rcp_f32_e32 v0, v0
	v_pk_mul_f32 v[24:25], v[24:25], v[178:179]
	v_add_f32_e32 v3, v16, v76
	v_add_f32_e32 v10, v17, v77
	v_cndmask_b32_e64 v17, 1.0, v174, s[38:39]
	v_cndmask_b32_e64 v16, 1.0, v173, s[38:39]
	v_cndmask_b32_e64 v25, 0, v25, s[38:39]
	v_cndmask_b32_e64 v24, 0, v24, s[38:39]
	v_mul_f32_e32 v0, v80, v0
	v_mul_f32_e32 v0, 0x3fb8aa3b, v0
	s_nop 1
	v_fmac_f32_dpp v24, v24, v16 row_shr:1 row_mask:0xf bank_mask:0xf
	v_fmac_f32_dpp v25, v25, v17 row_shr:1 row_mask:0xf bank_mask:0xf
	v_mul_f32_dpp v16, v16, v16 row_shr:1 row_mask:0xf bank_mask:0xf
	v_mul_f32_dpp v17, v17, v17 row_shr:1 row_mask:0xf bank_mask:0xf
	v_exp_f32_e32 v11, v0
	v_add_f32_e32 v0, v33, v73
	v_fmac_f32_dpp v24, v24, v16 row_shr:2 row_mask:0xf bank_mask:0xf
	v_fmac_f32_dpp v25, v25, v17 row_shr:2 row_mask:0xf bank_mask:0xf
	v_mul_f32_dpp v16, v16, v16 row_shr:2 row_mask:0xf bank_mask:0xf
	v_mul_f32_dpp v17, v17, v17 row_shr:2 row_mask:0xf bank_mask:0xf
	v_mul_f32_e32 v5, v54, v5
	v_mul_f32_e32 v5, 0x3fb8aa3b, v5
	v_fmac_f32_dpp v24, v24, v16 row_shr:4 row_mask:0xf bank_mask:0xf
	v_fmac_f32_dpp v25, v25, v17 row_shr:4 row_mask:0xf bank_mask:0xf
	v_mul_f32_dpp v16, v16, v16 row_shr:4 row_mask:0xf bank_mask:0xf
	v_mul_f32_dpp v17, v17, v17 row_shr:4 row_mask:0xf bank_mask:0xf
	v_exp_f32_e32 v185, v5
	v_and_b32_e32 v181, 0xffff0000, v87
	v_lshlrev_b32_e32 v180, 16, v87
	v_cndmask_b32_e64 v87, v193, 1.0, vcc
	v_cndmask_b32_e64 v86, v191, 1.0, vcc
	v_fmac_f32_dpp v24, v24, v16 row_shr:8 row_mask:0xf bank_mask:0xf
	v_fmac_f32_dpp v25, v25, v17 row_shr:8 row_mask:0xf bank_mask:0xf
	v_mul_f32_dpp v16, v16, v16 row_shr:8 row_mask:0xf bank_mask:0xf
	v_mul_f32_dpp v17, v17, v17 row_shr:8 row_mask:0xf bank_mask:0xf
	v_pk_mul_f32 v[22:23], v[22:23], v[86:87]
	v_pk_mul_f32 v[22:23], v[22:23], v[180:181]
	v_fmac_f32_dpp v24, v24, v16 row_bcast:15 row_mask:0xa bank_mask:0xf
	v_fmac_f32_dpp v25, v25, v17 row_bcast:15 row_mask:0xa bank_mask:0xf
	v_mul_f32_dpp v16, v16, v16 row_bcast:15 row_mask:0xa bank_mask:0xf
	v_mul_f32_dpp v17, v17, v17 row_bcast:15 row_mask:0xa bank_mask:0xf
	v_mov_b32_e32 v174, v24
	v_mov_b32_e32 v175, v25
	v_mov_b32_e32 v172, v16
	v_mov_b32_e32 v173, v17
	v_cndmask_b32_e64 v17, 1.0, v183, s[38:39]
	v_cndmask_b32_e64 v16, 1.0, v182, s[38:39]
	v_cndmask_b32_e64 v23, 0, v23, s[38:39]
	v_cndmask_b32_e64 v22, 0, v22, s[38:39]
	v_fma_f32 v5, -v185, v185, 1.0
	v_max_f32_e32 v5, 0, v5
	s_nop 1
	v_fmac_f32_dpp v22, v22, v16 row_shr:1 row_mask:0xf bank_mask:0xf
	v_fmac_f32_dpp v23, v23, v17 row_shr:1 row_mask:0xf bank_mask:0xf
	v_mul_f32_dpp v16, v16, v16 row_shr:1 row_mask:0xf bank_mask:0xf
	v_mul_f32_dpp v17, v17, v17 row_shr:1 row_mask:0xf bank_mask:0xf
	v_sqrt_f32_e32 v198, v5
	v_fmac_f32_dpp v22, v22, v16 row_shr:2 row_mask:0xf bank_mask:0xf
	v_fmac_f32_dpp v23, v23, v17 row_shr:2 row_mask:0xf bank_mask:0xf
	v_mul_f32_dpp v16, v16, v16 row_shr:2 row_mask:0xf bank_mask:0xf
	v_mul_f32_dpp v17, v17, v17 row_shr:2 row_mask:0xf bank_mask:0xf
	v_fmac_f32_dpp v22, v22, v16 row_shr:4 row_mask:0xf bank_mask:0xf
	v_fmac_f32_dpp v23, v23, v17 row_shr:4 row_mask:0xf bank_mask:0xf
	v_mul_f32_dpp v16, v16, v16 row_shr:4 row_mask:0xf bank_mask:0xf
	v_mul_f32_dpp v17, v17, v17 row_shr:4 row_mask:0xf bank_mask:0xf
	v_cndmask_b32_e64 v183, v199, 1.0, vcc
	v_cndmask_b32_e64 v182, v198, 1.0, vcc
	v_fmac_f32_dpp v22, v22, v16 row_shr:8 row_mask:0xf bank_mask:0xf
	v_fmac_f32_dpp v23, v23, v17 row_shr:8 row_mask:0xf bank_mask:0xf
	v_mul_f32_dpp v16, v16, v16 row_shr:8 row_mask:0xf bank_mask:0xf
	v_mul_f32_dpp v17, v17, v17 row_shr:8 row_mask:0xf bank_mask:0xf
	v_and_b32_e32 v181, 0xffff0000, v88
	v_lshlrev_b32_e32 v180, 16, v88
	v_pk_mul_f32 v[20:21], v[20:21], v[182:183]
; #define SCAN_STEP(CTRL, RM) do { _Pragma("unroll") for (int r = 0; r < 16; ++r) { const float ap = DPP_F(1.0f, av[r], CTRL, RM), up = DPP_F(0.0f, uv[r], CTRL, RM); uv[r] = __builtin_fmaf(av[r], up, uv[r]); av[r] = av[r] * ap; } } while (0)
; __device__ __forceinline__ void rec_et(LAS unsigned char* lds, const RecArgs& a, const bf16_t* Wr, const bf16_t* Wi, const int et, const int n, const int r32, const int hi, ...
;     ...
;                 SCAN_STEP(0x111, 0xf); SCAN_STEP(0x112, 0xf); SCAN_STEP(0x114, 0xf); SCAN_STEP(0x118, 0xf);
;                 SCAN_STEP(0x142, 0xa);
	v_pk_mul_f32 v[20:21], v[20:21], v[180:181]
	v_fmac_f32_dpp v22, v22, v16 row_bcast:15 row_mask:0xa bank_mask:0xf
	v_fmac_f32_dpp v23, v23, v17 row_bcast:15 row_mask:0xa bank_mask:0xf
	v_mul_f32_dpp v16, v16, v16 row_bcast:15 row_mask:0xa bank_mask:0xf
	v_mul_f32_dpp v17, v17, v17 row_bcast:15 row_mask:0xa bank_mask:0xf
	v_mov_b32_e32 v86, v22
	v_mov_b32_e32 v87, v23
	v_mov_b32_e32 v176, v16
	v_mov_b32_e32 v177, v17
	v_cndmask_b32_e64 v17, 1.0, v189, s[38:39]
	v_cndmask_b32_e64 v16, 1.0, v185, s[38:39]
	v_cndmask_b32_e64 v21, 0, v21, s[38:39]
	v_cndmask_b32_e64 v20, 0, v20, s[38:39]
	s_nop 1
	v_fmac_f32_dpp v20, v20, v16 row_shr:1 row_mask:0xf bank_mask:0xf
	v_fmac_f32_dpp v21, v21, v17 row_shr:1 row_mask:0xf bank_mask:0xf
	v_mul_f32_dpp v16, v16, v16 row_shr:1 row_mask:0xf bank_mask:0xf
	v_mul_f32_dpp v17, v17, v17 row_shr:1 row_mask:0xf bank_mask:0xf
	v_fmac_f32_dpp v20, v20, v16 row_shr:2 row_mask:0xf bank_mask:0xf
	v_fmac_f32_dpp v21, v21, v17 row_shr:2 row_mask:0xf bank_mask:0xf
	v_mul_f32_dpp v16, v16, v16 row_shr:2 row_mask:0xf bank_mask:0xf
	v_mul_f32_dpp v17, v17, v17 row_shr:2 row_mask:0xf bank_mask:0xf
	v_fmac_f32_dpp v20, v20, v16 row_shr:4 row_mask:0xf bank_mask:0xf
	v_fmac_f32_dpp v21, v21, v17 row_shr:4 row_mask:0xf bank_mask:0xf
	v_mul_f32_dpp v16, v16, v16 row_shr:4 row_mask:0xf bank_mask:0xf
	v_mul_f32_dpp v17, v17, v17 row_shr:4 row_mask:0xf bank_mask:0xf
	v_fmac_f32_dpp v20, v20, v16 row_shr:8 row_mask:0xf bank_mask:0xf
	v_fmac_f32_dpp v21, v21, v17 row_shr:8 row_mask:0xf bank_mask:0xf
	v_mul_f32_dpp v16, v16, v16 row_shr:8 row_mask:0xf bank_mask:0xf
	v_mul_f32_dpp v17, v17, v17 row_shr:8 row_mask:0xf bank_mask:0xf
	v_fmac_f32_dpp v20, v20, v16 row_bcast:15 row_mask:0xa bank_mask:0xf
	v_fmac_f32_dpp v21, v21, v17 row_bcast:15 row_mask:0xa bank_mask:0xf
	v_mul_f32_dpp v16, v16, v16 row_bcast:15 row_mask:0xa bank_mask:0xf
	v_mul_f32_dpp v17, v17, v17 row_bcast:15 row_mask:0xa bank_mask:0xf
	v_mov_b32_e32 v180, v20
	v_mov_b32_e32 v181, v21
	v_mov_b32_e32 v178, v16
	v_mov_b32_e32 v179, v17
	v_cndmask_b32_e64 v17, 1.0, v200, s[38:39]
	v_cndmask_b32_e64 v16, 1.0, v190, s[38:39]
	v_cndmask_b32_e64 v88, v201, 1.0, vcc
	v_and_b32_e32 v33, 0xffff0000, v89
	v_lshlrev_b32_e32 v32, 16, v89
	v_cndmask_b32_e64 v89, v202, 1.0, vcc
	v_pk_mul_f32 v[18:19], v[18:19], v[88:89]
	v_mul_f32_e32 v2, 0xbfb8aa3b, v2
	v_pk_mul_f32 v[18:19], v[18:19], v[32:33]
	v_cndmask_b32_e64 v19, 0, v19, s[38:39]
	v_cndmask_b32_e64 v18, 0, v18, s[38:39]
	v_exp_f32_e32 v2, v2
	s_nop 1
	v_fmac_f32_dpp v18, v18, v16 row_shr:1 row_mask:0xf bank_mask:0xf
	v_fmac_f32_dpp v19, v19, v17 row_shr:1 row_mask:0xf bank_mask:0xf
	v_mul_f32_dpp v16, v16, v16 row_shr:1 row_mask:0xf bank_mask:0xf
	v_mul_f32_dpp v17, v17, v17 row_shr:1 row_mask:0xf bank_mask:0xf
	v_cndmask_b32_e64 v33, v187, 1.0, vcc
	v_fmac_f32_dpp v18, v18, v16 row_shr:2 row_mask:0xf bank_mask:0xf
	v_fmac_f32_dpp v19, v19, v17 row_shr:2 row_mask:0xf bank_mask:0xf
	v_mul_f32_dpp v16, v16, v16 row_shr:2 row_mask:0xf bank_mask:0xf
	v_mul_f32_dpp v17, v17, v17 row_shr:2 row_mask:0xf bank_mask:0xf
	v_fmac_f32_dpp v18, v18, v16 row_shr:4 row_mask:0xf bank_mask:0xf
	v_fmac_f32_dpp v19, v19, v17 row_shr:4 row_mask:0xf bank_mask:0xf
	v_mul_f32_dpp v16, v16, v16 row_shr:4 row_mask:0xf bank_mask:0xf
	v_mul_f32_dpp v17, v17, v17 row_shr:4 row_mask:0xf bank_mask:0xf
	v_fmac_f32_dpp v18, v18, v16 row_shr:8 row_mask:0xf bank_mask:0xf
	v_fmac_f32_dpp v19, v19, v17 row_shr:8 row_mask:0xf bank_mask:0xf
	v_mul_f32_dpp v16, v16, v16 row_shr:8 row_mask:0xf bank_mask:0xf
	v_mul_f32_dpp v17, v17, v17 row_shr:8 row_mask:0xf bank_mask:0xf
	v_fmac_f32_dpp v18, v18, v16 row_bcast:15 row_mask:0xa bank_mask:0xf
	v_fmac_f32_dpp v19, v19, v17 row_bcast:15 row_mask:0xa bank_mask:0xf
	v_mul_f32_dpp v16, v16, v16 row_bcast:15 row_mask:0xa bank_mask:0xf
	v_mul_f32_dpp v17, v17, v17 row_bcast:15 row_mask:0xa bank_mask:0xf
	v_mov_b32_e32 v88, v18
	v_mov_b32_e32 v89, v19
	v_mov_b32_e32 v182, v16
	v_mov_b32_e32 v183, v17
	v_cndmask_b32_e64 v17, 1.0, v203, s[38:39]
	v_cndmask_b32_e64 v16, 1.0, v184, s[38:39]
	v_cndmask_b32_e64 v32, v186, 1.0, vcc
	v_pk_mul_f32 v[8:9], v[8:9], v[32:33]
	v_add_f32_e32 v2, 1.0, v2
	v_rcp_f32_e32 v5, v2
	s_waitcnt lgkmcnt(0)
	v_and_b32_e32 v31, 0xffff0000, v82
	v_lshlrev_b32_e32 v30, 16, v82
	v_pk_mul_f32 v[8:9], v[8:9], v[30:31]
	v_cndmask_b32_e64 v9, 0, v9, s[38:39]
	v_cndmask_b32_e64 v8, 0, v8, s[38:39]
	v_fma_f32 v2, -v15, v15, 1.0
	s_nop 1
	v_fmac_f32_dpp v8, v8, v16 row_shr:1 row_mask:0xf bank_mask:0xf
	v_fmac_f32_dpp v9, v9, v17 row_shr:1 row_mask:0xf bank_mask:0xf
	v_mul_f32_dpp v16, v16, v16 row_shr:1 row_mask:0xf bank_mask:0xf
	v_mul_f32_dpp v17, v17, v17 row_shr:1 row_mask:0xf bank_mask:0xf
	v_max_f32_e32 v2, 0, v2
	v_fmac_f32_dpp v8, v8, v16 row_shr:2 row_mask:0xf bank_mask:0xf
	v_fmac_f32_dpp v9, v9, v17 row_shr:2 row_mask:0xf bank_mask:0xf
	v_mul_f32_dpp v16, v16, v16 row_shr:2 row_mask:0xf bank_mask:0xf
	v_mul_f32_dpp v17, v17, v17 row_shr:2 row_mask:0xf bank_mask:0xf
	v_fmac_f32_dpp v8, v8, v16 row_shr:4 row_mask:0xf bank_mask:0xf
	v_fmac_f32_dpp v9, v9, v17 row_shr:4 row_mask:0xf bank_mask:0xf
	v_mul_f32_dpp v16, v16, v16 row_shr:4 row_mask:0xf bank_mask:0xf
	v_mul_f32_dpp v17, v17, v17 row_shr:4 row_mask:0xf bank_mask:0xf
	v_fmac_f32_dpp v8, v8, v16 row_shr:8 row_mask:0xf bank_mask:0xf
	v_fmac_f32_dpp v9, v9, v17 row_shr:8 row_mask:0xf bank_mask:0xf
	v_mul_f32_dpp v16, v16, v16 row_shr:8 row_mask:0xf bank_mask:0xf
	v_mul_f32_dpp v17, v17, v17 row_shr:8 row_mask:0xf bank_mask:0xf
	v_fmac_f32_dpp v8, v8, v16 row_bcast:15 row_mask:0xa bank_mask:0xf
	v_fmac_f32_dpp v9, v9, v17 row_bcast:15 row_mask:0xa bank_mask:0xf
; #define SCAN_STEP(CTRL, RM) do { _Pragma("unroll") for (int r = 0; r < 16; ++r) { const float ap = DPP_F(1.0f, av[r], CTRL, RM), up = DPP_F(0.0f, uv[r], CTRL, RM); uv[r] = __builtin_fmaf(av[r], up, uv[r]); av[r] = av[r] * ap; } } while (0)
; __device__ __forceinline__ void rec_et(LAS unsigned char* lds, const RecArgs& a, const bf16_t* Wr, const bf16_t* Wi, const int et, const int n, const int r32, const int hi, ...
;     ...
;                 SCAN_STEP(0x111, 0xf); SCAN_STEP(0x112, 0xf); SCAN_STEP(0x114, 0xf); SCAN_STEP(0x118, 0xf);
;                 SCAN_STEP(0x142, 0xa);
;     ...
;                 if (tt == 0) {
; #pragma unroll
;                     for (int r = 0; r < 16; ++r) { A0[r] = __shfl(av[r], 31, 32); H0[r] = __shfl(uv[r], 31, 32); }
	v_mul_f32_dpp v16, v16, v16 row_bcast:15 row_mask:0xa bank_mask:0xf
	v_mul_f32_dpp v17, v17, v17 row_bcast:15 row_mask:0xa bank_mask:0xf
	v_mov_b32_e32 v186, v8
	v_mov_b32_e32 v187, v9
	v_mov_b32_e32 v184, v16
	v_mov_b32_e32 v185, v17
	v_cndmask_b32_e64 v9, 1.0, v29, s[38:39]
	v_cndmask_b32_e64 v8, 1.0, v188, s[38:39]
	v_cndmask_b32_e64 v29, v28, 1.0, vcc
	v_cndmask_b32_e64 v28, v27, 1.0, vcc
	v_pk_mul_f32 v[6:7], v[6:7], v[28:29]
	v_sqrt_f32_e32 v14, v2
	v_and_b32_e32 v25, 0xffff0000, v83
	v_lshlrev_b32_e32 v24, 16, v83
	v_pk_mul_f32 v[6:7], v[6:7], v[24:25]
	v_cndmask_b32_e64 v7, 0, v7, s[38:39]
	v_cndmask_b32_e64 v6, 0, v6, s[38:39]
	v_mul_f32_e32 v0, 0xbfb8aa3b, v0
	s_nop 1
	v_fmac_f32_dpp v6, v6, v8 row_shr:1 row_mask:0xf bank_mask:0xf
	v_fmac_f32_dpp v7, v7, v9 row_shr:1 row_mask:0xf bank_mask:0xf
	v_mul_f32_dpp v8, v8, v8 row_shr:1 row_mask:0xf bank_mask:0xf
	v_mul_f32_dpp v9, v9, v9 row_shr:1 row_mask:0xf bank_mask:0xf
	v_exp_f32_e32 v0, v0
	v_fmac_f32_dpp v6, v6, v8 row_shr:2 row_mask:0xf bank_mask:0xf
	v_fmac_f32_dpp v7, v7, v9 row_shr:2 row_mask:0xf bank_mask:0xf
	v_mul_f32_dpp v8, v8, v8 row_shr:2 row_mask:0xf bank_mask:0xf
	v_mul_f32_dpp v9, v9, v9 row_shr:2 row_mask:0xf bank_mask:0xf
	v_fmac_f32_dpp v6, v6, v8 row_shr:4 row_mask:0xf bank_mask:0xf
	v_fmac_f32_dpp v7, v7, v9 row_shr:4 row_mask:0xf bank_mask:0xf
	v_mul_f32_dpp v8, v8, v8 row_shr:4 row_mask:0xf bank_mask:0xf
	v_mul_f32_dpp v9, v9, v9 row_shr:4 row_mask:0xf bank_mask:0xf
	v_fmac_f32_dpp v6, v6, v8 row_shr:8 row_mask:0xf bank_mask:0xf
	v_fmac_f32_dpp v7, v7, v9 row_shr:8 row_mask:0xf bank_mask:0xf
	v_mul_f32_dpp v8, v8, v8 row_shr:8 row_mask:0xf bank_mask:0xf
	v_mul_f32_dpp v9, v9, v9 row_shr:8 row_mask:0xf bank_mask:0xf
	v_fmac_f32_dpp v6, v6, v8 row_bcast:15 row_mask:0xa bank_mask:0xf
	v_fmac_f32_dpp v7, v7, v9 row_bcast:15 row_mask:0xa bank_mask:0xf
	v_mul_f32_dpp v8, v8, v8 row_bcast:15 row_mask:0xa bank_mask:0xf
	v_mul_f32_dpp v9, v9, v9 row_bcast:15 row_mask:0xa bank_mask:0xf
	v_mov_b32_e32 v82, v6
	v_mov_b32_e32 v83, v7
	v_mov_b32_e32 v188, v8
	v_mov_b32_e32 v189, v9
	v_cndmask_b32_e64 v7, 1.0, v15, s[38:39]
	v_cndmask_b32_e64 v6, 1.0, v26, s[38:39]
	v_cndmask_b32_e64 v15, v14, 1.0, vcc
	v_cndmask_b32_e64 v14, v12, 1.0, vcc
	v_pk_mul_f32 v[4:5], v[4:5], v[14:15]
	v_add_f32_e32 v0, 1.0, v0
	v_and_b32_e32 v23, 0xffff0000, v84
	v_lshlrev_b32_e32 v22, 16, v84
	v_pk_mul_f32 v[4:5], v[4:5], v[22:23]
	v_rcp_f32_e32 v0, v0
	v_cndmask_b32_e64 v5, 0, v5, s[38:39]
	v_cndmask_b32_e64 v4, 0, v4, s[38:39]
	v_mul_f32_e32 v0, v81, v0
	s_nop 1
	v_fmac_f32_dpp v4, v4, v6 row_shr:1 row_mask:0xf bank_mask:0xf
	v_fmac_f32_dpp v5, v5, v7 row_shr:1 row_mask:0xf bank_mask:0xf
	v_mul_f32_dpp v6, v6, v6 row_shr:1 row_mask:0xf bank_mask:0xf
	v_mul_f32_dpp v7, v7, v7 row_shr:1 row_mask:0xf bank_mask:0xf
	v_mul_f32_e32 v0, 0x3fb8aa3b, v0
	v_fmac_f32_dpp v4, v4, v6 row_shr:2 row_mask:0xf bank_mask:0xf
	v_fmac_f32_dpp v5, v5, v7 row_shr:2 row_mask:0xf bank_mask:0xf
	v_mul_f32_dpp v6, v6, v6 row_shr:2 row_mask:0xf bank_mask:0xf
	v_mul_f32_dpp v7, v7, v7 row_shr:2 row_mask:0xf bank_mask:0xf
	v_mul_f32_e32 v3, 0xbfb8aa3b, v3
	v_exp_f32_e32 v13, v0
	v_fmac_f32_dpp v4, v4, v6 row_shr:4 row_mask:0xf bank_mask:0xf
	v_fmac_f32_dpp v5, v5, v7 row_shr:4 row_mask:0xf bank_mask:0xf
	v_mul_f32_dpp v6, v6, v6 row_shr:4 row_mask:0xf bank_mask:0xf
	v_mul_f32_dpp v7, v7, v7 row_shr:4 row_mask:0xf bank_mask:0xf
	v_exp_f32_e32 v3, v3
	v_mul_f32_e32 v10, 0xbfb8aa3b, v10
	v_fmac_f32_dpp v4, v4, v6 row_shr:8 row_mask:0xf bank_mask:0xf
	v_fmac_f32_dpp v5, v5, v7 row_shr:8 row_mask:0xf bank_mask:0xf
	v_mul_f32_dpp v6, v6, v6 row_shr:8 row_mask:0xf bank_mask:0xf
	v_mul_f32_dpp v7, v7, v7 row_shr:8 row_mask:0xf bank_mask:0xf
	v_exp_f32_e32 v10, v10
	v_fmac_f32_dpp v4, v4, v6 row_bcast:15 row_mask:0xa bank_mask:0xf
	v_fmac_f32_dpp v5, v5, v7 row_bcast:15 row_mask:0xa bank_mask:0xf
	v_mul_f32_dpp v6, v6, v6 row_bcast:15 row_mask:0xa bank_mask:0xf
	v_mul_f32_dpp v7, v7, v7 row_bcast:15 row_mask:0xa bank_mask:0xf
	v_mov_b32_e32 v202, v4
	v_mov_b32_e32 v203, v5
	v_mov_b32_e32 v190, v6
	v_mov_b32_e32 v191, v7
	v_cndmask_b32_e64 v5, 1.0, v13, s[38:39]
	v_cndmask_b32_e64 v4, 1.0, v11, s[38:39]
	v_add_f32_e32 v2, 1.0, v3
	v_fma_f32 v3, -v11, v11, 1.0
	v_max_f32_e32 v3, 0, v3
	v_sqrt_f32_e32 v0, v3
	v_add_f32_e32 v3, 1.0, v10
	v_fma_f32 v10, -v13, v13, 1.0
	v_max_f32_e32 v10, 0, v10
	v_sqrt_f32_e32 v10, v10
	v_rcp_f32_e32 v2, v2
	v_rcp_f32_e32 v3, v3
	v_cndmask_b32_e64 v11, v10, 1.0, vcc
	v_cndmask_b32_e64 v10, v0, 1.0, vcc
	v_and_b32_e32 v17, 0xffff0000, v85
	v_lshlrev_b32_e32 v16, 16, v85
	v_pk_mul_f32 v[2:3], v[2:3], v[10:11]
	v_pk_mul_f32 v[2:3], v[2:3], v[16:17]
	v_cndmask_b32_e64 v3, 0, v3, s[38:39]
	v_cndmask_b32_e64 v2, 0, v2, s[38:39]
	s_nop 0
	s_nop 1
	v_fmac_f32_dpp v2, v2, v4 row_shr:1 row_mask:0xf bank_mask:0xf
	v_fmac_f32_dpp v3, v3, v5 row_shr:1 row_mask:0xf bank_mask:0xf
	v_mul_f32_dpp v4, v4, v4 row_shr:1 row_mask:0xf bank_mask:0xf
	v_mul_f32_dpp v5, v5, v5 row_shr:1 row_mask:0xf bank_mask:0xf
	s_nop 0
	v_fmac_f32_dpp v2, v2, v4 row_shr:2 row_mask:0xf bank_mask:0xf
	v_fmac_f32_dpp v3, v3, v5 row_shr:2 row_mask:0xf bank_mask:0xf
	v_mul_f32_dpp v4, v4, v4 row_shr:2 row_mask:0xf bank_mask:0xf
	v_mul_f32_dpp v5, v5, v5 row_shr:2 row_mask:0xf bank_mask:0xf
	s_nop 0
	v_fmac_f32_dpp v2, v2, v4 row_shr:4 row_mask:0xf bank_mask:0xf
	v_fmac_f32_dpp v3, v3, v5 row_shr:4 row_mask:0xf bank_mask:0xf
	v_mul_f32_dpp v4, v4, v4 row_shr:4 row_mask:0xf bank_mask:0xf
	v_mul_f32_dpp v5, v5, v5 row_shr:4 row_mask:0xf bank_mask:0xf
	s_nop 0
	v_fmac_f32_dpp v2, v2, v4 row_shr:8 row_mask:0xf bank_mask:0xf
	v_fmac_f32_dpp v3, v3, v5 row_shr:8 row_mask:0xf bank_mask:0xf
	v_mul_f32_dpp v4, v4, v4 row_shr:8 row_mask:0xf bank_mask:0xf
	v_mul_f32_dpp v5, v5, v5 row_shr:8 row_mask:0xf bank_mask:0xf
	s_nop 0
	v_fmac_f32_dpp v2, v2, v4 row_bcast:15 row_mask:0xa bank_mask:0xf
	v_fmac_f32_dpp v3, v3, v5 row_bcast:15 row_mask:0xa bank_mask:0xf
	v_mul_f32_dpp v4, v4, v4 row_bcast:15 row_mask:0xa bank_mask:0xf
	v_mul_f32_dpp v5, v5, v5 row_bcast:15 row_mask:0xa bank_mask:0xf
	v_mov_b32_e32 v84, v2
	v_mov_b32_e32 v85, v3
	v_mov_b32_e32 v204, v4
	v_mov_b32_e32 v205, v5
	s_cbranch_scc1 .LBB0_480
; __device__ __forceinline__ void rec_et(LAS unsigned char* lds, const RecArgs& a, const bf16_t* Wr, const bf16_t* Wi, const int et, const int n, const int r32, const int hi, ...
;     ...
; #pragma unroll
;                     for (int r = 0; r < 16; ++r) { uv[r] = av[r] * H0[r] + uv[r]; av[r] = av[r] * A0[r]; }
;                 }
	v_pk_fma_f32 v[4:5], v[170:171], v[204:205], v[84:85] op_sel:[1,0,0] op_sel_hi:[0,1,1]
	v_pk_mul_f32 v[8:9], v[168:169], v[204:205] op_sel:[1,0] op_sel_hi:[0,1]
	v_pk_fma_f32 v[26:27], v[142:143], v[172:173], v[174:175] op_sel:[1,0,0] op_sel_hi:[0,1,1]
	v_pk_mul_f32 v[30:31], v[140:141], v[172:173] op_sel:[1,0] op_sel_hi:[0,1]
	v_pk_fma_f32 v[28:29], v[146:147], v[176:177], v[86:87] op_sel:[1,0,0] op_sel_hi:[0,1,1]
	v_pk_mul_f32 v[32:33], v[144:145], v[176:177] op_sel:[1,0] op_sel_hi:[0,1]
	v_pk_fma_f32 v[18:19], v[150:151], v[178:179], v[180:181] op_sel:[1,0,0] op_sel_hi:[0,1,1]
	v_pk_mul_f32 v[22:23], v[148:149], v[178:179] op_sel:[1,0] op_sel_hi:[0,1]
	v_pk_fma_f32 v[20:21], v[154:155], v[182:183], v[88:89] op_sel:[1,0,0] op_sel_hi:[0,1,1]
	v_pk_mul_f32 v[24:25], v[152:153], v[182:183] op_sel:[1,0] op_sel_hi:[0,1]
	v_pk_fma_f32 v[10:11], v[158:159], v[184:185], v[186:187] op_sel:[1,0,0] op_sel_hi:[0,1,1]
	v_pk_mul_f32 v[14:15], v[156:157], v[184:185] op_sel:[1,0] op_sel_hi:[0,1]
	v_pk_fma_f32 v[12:13], v[162:163], v[188:189], v[82:83] op_sel:[1,0,0] op_sel_hi:[0,1,1]
	v_pk_mul_f32 v[16:17], v[160:161], v[188:189] op_sel:[1,0] op_sel_hi:[0,1]
	v_pk_fma_f32 v[2:3], v[166:167], v[190:191], v[202:203] op_sel:[1,0,0] op_sel_hi:[0,1,1]
	v_pk_mul_f32 v[6:7], v[164:165], v[190:191] op_sel:[1,0] op_sel_hi:[0,1]
	v_mov_b64_e32 v[206:207], v[8:9]
	v_mov_b64_e32 v[208:209], v[4:5]
	s_cbranch_execnz .LBB0_476

; #define LAS __attribute__((address_space(3)))
; __device__ __forceinline__ float bf2f(unsigned short v) { return __uint_as_float((unsigned)v << 16); }
; __device__ __forceinline__ void rec_et(LAS unsigned char* lds, const RecArgs& a, const bf16_t* Wr, const bf16_t* Wi, const int et, const int n, const int r32, const int hi, ...
;     ...
;                 for (int kk = 0; kk < 4; ++kk) { const bf16x8 xb = *(const LAS bf16x8*)(lds + (32 * tt + r32) * XC_STRIDE + (64 * n + 16 * kk + 8 * hi) * 2);
;                     const bf16x8 war = *(const bf16x8*)(Wr + (32 * et + r32) * 64 + 16 * kk + 8 * hi), wai = *(const bf16x8*)(Wi + (32 * et + r32) * 64 + 16 * kk + 8 * hi);
;                     accr = __builtin_amdgcn_mfma_f32_32x32x16_bf16(war, xb, accr, 0, 0, 0);
;                     acci = __builtin_amdgcn_mfma_f32_32x32x16_bf16(wai, xb, acci, 0, 0, 0); }
;                 const int tok = 32 * tt + r32, t = t0 + tok; const bool valid = tok < nvalid;
;                 float av[16], uv[16];
; #pragma unroll
;                 for (int r = 0; r < 16; ++r) { const int ch = 64 * n + 32 * et + (r & 3) + 8 * (r >> 2) + 4 * hi;
;                     const float xcv = bf2f(*(const LAS unsigned short*)(lds + tok * XC_STRIDE + ch * 2));
;                     const float rg = __builtin_amdgcn_rcpf(1.0f + __expf(-(accr[r] + Pbrg[ch]))), ig = __builtin_amdgcn_rcpf(1.0f + __expf(-(acci[r] + Pbig[ch])));
;                     const float la = rg * Plsl[ch]; float aa = __expf(la); float mult = __builtin_amdgcn_sqrtf(fmaxf(__builtin_fmaf(-aa, aa, 1.0f), 0.f)); if (t == 0) mult = 1.0f;
;                     float uu = mult * ig * xcv; if (!valid) { aa = 1.0f; uu = 0.f; }
;                     av[r] = aa; uv[r] = uu; }
.LBB0_483:
	global_load_dwordx4 v[2:5], v[102:103], off
	global_load_dwordx4 v[6:9], v[104:105], off
	global_load_dwordx4 v[82:85], v[102:103], off offset:32
	ds_read_b128 v[10:13], v248
	ds_read_b128 v[86:89], v248 offset:32
	global_load_dwordx4 v[172:175], v[104:105], off offset:32
	global_load_dwordx4 v[176:179], v[102:103], off offset:64
	v_cmp_eq_u32_e32 vcc, s21, v250
	v_cmp_gt_u32_e64 s[38:39], s14, v250
	s_cmp_eq_u32 s10, 0
	s_waitcnt vmcnt(4) lgkmcnt(1)
	v_mfma_f32_32x32x16_bf16 v[18:33], v[2:5], v[10:13], 0
	s_waitcnt vmcnt(3)
	v_mfma_f32_32x32x16_bf16 v[2:17], v[6:9], v[10:13], 0
	s_waitcnt vmcnt(2) lgkmcnt(0)
	v_mfma_f32_32x32x16_bf16 v[18:33], v[82:85], v[86:89], v[18:33]
	global_load_dwordx4 v[82:85], v[104:105], off offset:64
	s_waitcnt vmcnt(2)
	v_mfma_f32_32x32x16_bf16 v[2:17], v[172:175], v[86:89], v[2:17]
	global_load_dwordx4 v[86:89], v[102:103], off offset:96
	ds_read_b128 v[172:175], v248 offset:64
	ds_read_b128 v[180:183], v248 offset:96
	s_waitcnt vmcnt(2) lgkmcnt(1)
	v_mfma_f32_32x32x16_bf16 v[18:33], v[176:179], v[172:175], v[18:33]
	global_load_dwordx4 v[176:179], v[104:105], off offset:96
	s_waitcnt vmcnt(2)
	v_mfma_f32_32x32x16_bf16 v[2:17], v[82:85], v[172:175], v[2:17]
	s_waitcnt vmcnt(1) lgkmcnt(0)
	v_mfma_f32_32x32x16_bf16 v[18:33], v[86:89], v[180:183], v[18:33]
	ds_read2_b64 v[86:89], v249 offset1:2
	ds_read2_b64 v[82:85], v249 offset0:4 offset1:6
	s_waitcnt vmcnt(0)
	v_mfma_f32_32x32x16_bf16 v[2:17], v[176:179], v[180:183], v[2:17]
	s_nop 7
	v_add_f32_e32 v0, v18, v34
	v_add_f32_e32 v18, v19, v35
	v_mul_f32_e32 v0, 0xbfb8aa3b, v0
	v_mul_f32_e32 v18, 0xbfb8aa3b, v18
	v_exp_f32_e32 v0, v0
	v_exp_f32_e32 v18, v18
	v_add_f32_e32 v19, v20, v36
	v_add_f32_e32 v2, v2, v38
	v_mul_f32_e32 v2, 0xbfb8aa3b, v2
	v_exp_f32_e32 v2, v2
	v_add_f32_e32 v4, v4, v40
	v_add_f32_e32 v20, v21, v37
	v_add_f32_e32 v21, v22, v46
	v_add_f32_e32 v6, v6, v50
	v_add_f32_e32 v22, v23, v47
	v_add_f32_e32 v23, v24, v48
	v_add_f32_e32 v24, v25, v49
	v_add_f32_e32 v0, 1.0, v0
	v_add_f32_e32 v5, v5, v41
	v_add_f32_e32 v7, v7, v51
	v_mul_f32_e32 v4, 0xbfb8aa3b, v4
	v_mul_f32_e32 v20, 0xbfb8aa3b, v20
	v_mul_f32_e32 v6, 0xbfb8aa3b, v6
	v_mul_f32_e32 v22, 0xbfb8aa3b, v22
	v_mul_f32_e32 v24, 0xbfb8aa3b, v24
	v_add_f32_e32 v2, 1.0, v2
	v_add_f32_e32 v18, 1.0, v18
	v_rcp_f32_e32 v0, v0
	v_mul_f32_e32 v5, 0xbfb8aa3b, v5
	v_mul_f32_e32 v21, 0xbfb8aa3b, v21
	v_mul_f32_e32 v7, 0xbfb8aa3b, v7
	v_mul_f32_e32 v23, 0xbfb8aa3b, v23
	v_exp_f32_e32 v4, v4
	v_exp_f32_e32 v20, v20
	v_exp_f32_e32 v6, v6
	v_exp_f32_e32 v22, v22
	v_exp_f32_e32 v172, v24
	v_rcp_f32_e32 v24, v2
	v_rcp_f32_e32 v2, v18
	v_exp_f32_e32 v5, v5
	v_exp_f32_e32 v21, v21
	v_exp_f32_e32 v7, v7
	v_exp_f32_e32 v23, v23
	v_add_f32_e32 v3, v3, v39
	v_mul_f32_e32 v0, v42, v0
	v_mul_f32_e32 v3, 0xbfb8aa3b, v3
	v_mul_f32_e32 v19, 0xbfb8aa3b, v19
	v_add_f32_e32 v4, 1.0, v4
	v_add_f32_e32 v20, 1.0, v20
	v_add_f32_e32 v6, 1.0, v6
	v_add_f32_e32 v173, 1.0, v22
	v_mul_f32_e32 v2, v43, v2
	v_mul_f32_e32 v0, 0x3fb8aa3b, v0
	v_exp_f32_e32 v3, v3
	v_exp_f32_e32 v19, v19
	v_add_f32_e32 v5, 1.0, v5
	v_add_f32_e32 v21, 1.0, v21
	v_add_f32_e32 v7, 1.0, v7
	v_add_f32_e32 v174, 1.0, v23
	v_rcp_f32_e32 v22, v4
	v_rcp_f32_e32 v4, v20
	v_rcp_f32_e32 v20, v6
	v_rcp_f32_e32 v6, v173
	v_mul_f32_e32 v2, 0x3fb8aa3b, v2
	v_exp_f32_e32 v173, v0
	v_rcp_f32_e32 v23, v5
	v_rcp_f32_e32 v5, v21
	v_rcp_f32_e32 v21, v7
	v_rcp_f32_e32 v7, v174
	v_exp_f32_e32 v174, v2
	v_add_f32_e32 v3, 1.0, v3
	v_add_f32_e32 v19, 1.0, v19
	v_fma_f32 v0, -v173, v173, 1.0
	v_rcp_f32_e32 v25, v3
	v_rcp_f32_e32 v3, v19
	v_fma_f32 v2, -v174, v174, 1.0
	v_max_f32_e32 v0, 0, v0
	v_max_f32_e32 v2, 0, v2
	v_sqrt_f32_e32 v180, v0
	v_add_f32_e32 v0, 1.0, v172
	v_sqrt_f32_e32 v181, v2
	v_rcp_f32_e32 v0, v0
	v_add_f32_e32 v2, v9, v53
	v_mul_f32_e32 v2, 0xbfb8aa3b, v2
	v_mul_f32_e32 v3, v44, v3
	v_exp_f32_e32 v2, v2
	v_mul_f32_e32 v3, 0x3fb8aa3b, v3
	v_exp_f32_e32 v182, v3
	v_mul_f32_e32 v0, v57, v0
	v_mul_f32_e32 v0, 0x3fb8aa3b, v0
	v_exp_f32_e32 v200, v0
	v_add_f32_e32 v0, 1.0, v2
	v_add_f32_e32 v2, v26, v58
	v_mul_f32_e32 v2, 0xbfb8aa3b, v2
	v_fma_f32 v3, -v182, v182, 1.0
	v_exp_f32_e32 v2, v2
	v_max_f32_e32 v3, 0, v3
	v_add_f32_e32 v8, v8, v52
	v_sqrt_f32_e32 v191, v3
	v_add_f32_e32 v3, v10, v62
	v_mul_f32_e32 v8, 0xbfb8aa3b, v8
	v_mul_f32_e32 v3, 0xbfb8aa3b, v3
	v_exp_f32_e32 v8, v8
	v_exp_f32_e32 v3, v3
	v_add_f32_e32 v2, 1.0, v2
	v_rcp_f32_e32 v2, v2
	v_rcp_f32_e32 v19, v0
	v_fma_f32 v0, -v200, v200, 1.0
	v_max_f32_e32 v0, 0, v0
	v_add_f32_e32 v8, 1.0, v8
	v_sqrt_f32_e32 v202, v0
	v_add_f32_e32 v0, 1.0, v3
	v_rcp_f32_e32 v18, v8
	v_rcp_f32_e32 v8, v0
	v_mul_f32_e32 v0, v66, v2
	v_mul_f32_e32 v0, 0x3fb8aa3b, v0
	v_exp_f32_e32 v184, v0
	v_add_f32_e32 v0, v27, v59
	v_mul_f32_e32 v0, 0xbfb8aa3b, v0
	v_exp_f32_e32 v0, v0
	v_fma_f32 v2, -v184, v184, 1.0
	v_max_f32_e32 v2, 0, v2
	v_sqrt_f32_e32 v186, v2
	v_add_f32_e32 v0, 1.0, v0
	v_rcp_f32_e32 v0, v0
	v_add_f32_e32 v2, v11, v63
	v_mul_f32_e32 v2, 0xbfb8aa3b, v2
	v_mul_f32_e32 v6, v55, v6
	v_mul_f32_e32 v0, v67, v0
	v_mul_f32_e32 v0, 0x3fb8aa3b, v0
	v_exp_f32_e32 v203, v0
	v_add_f32_e32 v0, v28, v60
	v_mul_f32_e32 v0, 0xbfb8aa3b, v0
	v_exp_f32_e32 v0, v0
	v_exp_f32_e32 v2, v2
	v_mul_f32_e32 v6, 0x3fb8aa3b, v6
	v_add_f32_e32 v3, v12, v64
	v_add_f32_e32 v0, 1.0, v0
	v_rcp_f32_e32 v0, v0
	v_exp_f32_e32 v189, v6
	v_mul_f32_e32 v3, 0xbfb8aa3b, v3
	v_exp_f32_e32 v3, v3
	v_mul_f32_e32 v0, v68, v0
	v_mul_f32_e32 v0, 0x3fb8aa3b, v0
	v_exp_f32_e32 v188, v0
	v_add_f32_e32 v0, v29, v61
	v_mul_f32_e32 v0, 0xbfb8aa3b, v0
	v_exp_f32_e32 v0, v0
	v_add_f32_e32 v2, 1.0, v2
	v_rcp_f32_e32 v9, v2
	v_fma_f32 v2, -v203, v203, 1.0
; #define SCAN_STEP(CTRL, RM) do { _Pragma("unroll") for (int r = 0; r < 16; ++r) { const float ap = DPP_F(1.0f, av[r], CTRL, RM), up = DPP_F(0.0f, uv[r], CTRL, RM); uv[r] = __builtin_fmaf(av[r], up, uv[r]); av[r] = av[r] * ap; } } while (0)
; __device__ __forceinline__ void rec_et(LAS unsigned char* lds, const RecArgs& a, const bf16_t* Wr, const bf16_t* Wi, const int et, const int n, const int r32, const int hi, ...
;     ...
;                 SCAN_STEP(0x111, 0xf); SCAN_STEP(0x112, 0xf); SCAN_STEP(0x114, 0xf); SCAN_STEP(0x118, 0xf);
;                 SCAN_STEP(0x142, 0xa);
	v_fma_f32 v6, -v189, v189, 1.0
	v_max_f32_e32 v2, 0, v2
	v_max_f32_e32 v6, 0, v6
	v_sqrt_f32_e32 v187, v2
	v_add_f32_e32 v2, 1.0, v3
	v_add_f32_e32 v0, 1.0, v0
	v_sqrt_f32_e32 v199, v6
	v_rcp_f32_e32 v6, v2
	v_fma_f32 v2, -v188, v188, 1.0
	v_rcp_f32_e32 v0, v0
	v_add_f32_e32 v3, v13, v65
	v_max_f32_e32 v2, 0, v2
	v_mul_f32_e32 v3, 0xbfb8aa3b, v3
	v_mul_f32_e32 v7, v56, v7
	v_exp_f32_e32 v3, v3
	v_sqrt_f32_e32 v27, v2
	v_add_f32_e32 v2, v30, v70
	v_mul_f32_e32 v7, 0x3fb8aa3b, v7
	v_mul_f32_e32 v2, 0xbfb8aa3b, v2
	v_exp_f32_e32 v190, v7
	v_mul_f32_e32 v0, v69, v0
	v_exp_f32_e32 v2, v2
	v_mul_f32_e32 v4, v45, v4
	v_mul_f32_e32 v0, 0x3fb8aa3b, v0
	v_mul_f32_e32 v4, 0x3fb8aa3b, v4
	v_exp_f32_e32 v29, v0
	v_add_f32_e32 v0, 1.0, v3
	v_add_f32_e32 v3, v14, v74
	v_exp_f32_e32 v183, v4
	v_mul_f32_e32 v3, 0xbfb8aa3b, v3
	v_fma_f32 v7, -v190, v190, 1.0
	v_exp_f32_e32 v3, v3
	v_add_f32_e32 v2, 1.0, v2
	v_max_f32_e32 v7, 0, v7
	v_rcp_f32_e32 v2, v2
	v_sqrt_f32_e32 v201, v7
	v_rcp_f32_e32 v7, v0
	v_fma_f32 v0, -v29, v29, 1.0
	v_fma_f32 v4, -v183, v183, 1.0
	v_max_f32_e32 v0, 0, v0
	v_max_f32_e32 v4, 0, v4
	v_sqrt_f32_e32 v28, v0
	v_add_f32_e32 v0, 1.0, v3
	v_sqrt_f32_e32 v193, v4
	v_rcp_f32_e32 v4, v0
	v_mul_f32_e32 v0, v78, v2
	v_mul_f32_e32 v0, 0x3fb8aa3b, v0
	v_exp_f32_e32 v26, v0
	v_add_f32_e32 v0, v31, v71
	v_mul_f32_e32 v0, 0xbfb8aa3b, v0
	v_exp_f32_e32 v0, v0
	v_fma_f32 v2, -v26, v26, 1.0
	v_max_f32_e32 v2, 0, v2
	v_sqrt_f32_e32 v12, v2
	v_add_f32_e32 v0, 1.0, v0
	v_rcp_f32_e32 v0, v0
	v_add_f32_e32 v2, v15, v75
	v_cndmask_b32_e64 v181, v181, 1.0, vcc
	v_cndmask_b32_e64 v180, v180, 1.0, vcc
	v_mul_f32_e32 v0, v79, v0
	v_mul_f32_e32 v0, 0x3fb8aa3b, v0
	v_exp_f32_e32 v15, v0
	v_add_f32_e32 v0, v32, v72
	v_mul_f32_e32 v0, 0xbfb8aa3b, v0
	v_exp_f32_e32 v0, v0
	s_waitcnt lgkmcnt(1)
	v_and_b32_e32 v179, 0xffff0000, v86
	v_lshlrev_b32_e32 v178, 16, v86
	v_pk_mul_f32 v[24:25], v[24:25], v[180:181]
	v_add_f32_e32 v0, 1.0, v0
	v_rcp_f32_e32 v0, v0
	v_pk_mul_f32 v[24:25], v[24:25], v[178:179]
	v_add_f32_e32 v3, v16, v76
	v_add_f32_e32 v10, v17, v77
	v_cndmask_b32_e64 v17, 1.0, v174, s[38:39]
	v_cndmask_b32_e64 v16, 1.0, v173, s[38:39]
	v_cndmask_b32_e64 v25, 0, v25, s[38:39]
	v_cndmask_b32_e64 v24, 0, v24, s[38:39]
	v_mul_f32_e32 v0, v80, v0
	v_mul_f32_e32 v0, 0x3fb8aa3b, v0
	s_nop 1
	v_fmac_f32_dpp v24, v24, v16 row_shr:1 row_mask:0xf bank_mask:0xf
	v_fmac_f32_dpp v25, v25, v17 row_shr:1 row_mask:0xf bank_mask:0xf
	v_mul_f32_dpp v16, v16, v16 row_shr:1 row_mask:0xf bank_mask:0xf
	v_mul_f32_dpp v17, v17, v17 row_shr:1 row_mask:0xf bank_mask:0xf
	v_exp_f32_e32 v11, v0
	v_add_f32_e32 v0, v33, v73
	v_fmac_f32_dpp v24, v24, v16 row_shr:2 row_mask:0xf bank_mask:0xf
	v_fmac_f32_dpp v25, v25, v17 row_shr:2 row_mask:0xf bank_mask:0xf
	v_mul_f32_dpp v16, v16, v16 row_shr:2 row_mask:0xf bank_mask:0xf
	v_mul_f32_dpp v17, v17, v17 row_shr:2 row_mask:0xf bank_mask:0xf
	v_mul_f32_e32 v5, v54, v5
	v_mul_f32_e32 v5, 0x3fb8aa3b, v5
	v_fmac_f32_dpp v24, v24, v16 row_shr:4 row_mask:0xf bank_mask:0xf
	v_fmac_f32_dpp v25, v25, v17 row_shr:4 row_mask:0xf bank_mask:0xf
	v_mul_f32_dpp v16, v16, v16 row_shr:4 row_mask:0xf bank_mask:0xf
	v_mul_f32_dpp v17, v17, v17 row_shr:4 row_mask:0xf bank_mask:0xf
	v_exp_f32_e32 v185, v5
	v_and_b32_e32 v181, 0xffff0000, v87
	v_lshlrev_b32_e32 v180, 16, v87
	v_cndmask_b32_e64 v87, v193, 1.0, vcc
	v_cndmask_b32_e64 v86, v191, 1.0, vcc
	v_fmac_f32_dpp v24, v24, v16 row_shr:8 row_mask:0xf bank_mask:0xf
	v_fmac_f32_dpp v25, v25, v17 row_shr:8 row_mask:0xf bank_mask:0xf
	v_mul_f32_dpp v16, v16, v16 row_shr:8 row_mask:0xf bank_mask:0xf
	v_mul_f32_dpp v17, v17, v17 row_shr:8 row_mask:0xf bank_mask:0xf
	v_pk_mul_f32 v[22:23], v[22:23], v[86:87]
	v_pk_mul_f32 v[22:23], v[22:23], v[180:181]
	v_fmac_f32_dpp v24, v24, v16 row_bcast:15 row_mask:0xa bank_mask:0xf
	v_fmac_f32_dpp v25, v25, v17 row_bcast:15 row_mask:0xa bank_mask:0xf
	v_mul_f32_dpp v16, v16, v16 row_bcast:15 row_mask:0xa bank_mask:0xf
	v_mul_f32_dpp v17, v17, v17 row_bcast:15 row_mask:0xa bank_mask:0xf
	v_mov_b32_e32 v174, v24
	v_mov_b32_e32 v175, v25
	v_mov_b32_e32 v172, v16
	v_mov_b32_e32 v173, v17
	v_cndmask_b32_e64 v17, 1.0, v183, s[38:39]
	v_cndmask_b32_e64 v16, 1.0, v182, s[38:39]
	v_cndmask_b32_e64 v23, 0, v23, s[38:39]
	v_cndmask_b32_e64 v22, 0, v22, s[38:39]
	v_fma_f32 v5, -v185, v185, 1.0
	v_max_f32_e32 v5, 0, v5
	s_nop 1
	v_fmac_f32_dpp v22, v22, v16 row_shr:1 row_mask:0xf bank_mask:0xf
	v_fmac_f32_dpp v23, v23, v17 row_shr:1 row_mask:0xf bank_mask:0xf
	v_mul_f32_dpp v16, v16, v16 row_shr:1 row_mask:0xf bank_mask:0xf
	v_mul_f32_dpp v17, v17, v17 row_shr:1 row_mask:0xf bank_mask:0xf
	v_sqrt_f32_e32 v198, v5
	v_fmac_f32_dpp v22, v22, v16 row_shr:2 row_mask:0xf bank_mask:0xf
	v_fmac_f32_dpp v23, v23, v17 row_shr:2 row_mask:0xf bank_mask:0xf
	v_mul_f32_dpp v16, v16, v16 row_shr:2 row_mask:0xf bank_mask:0xf
	v_mul_f32_dpp v17, v17, v17 row_shr:2 row_mask:0xf bank_mask:0xf
	v_fmac_f32_dpp v22, v22, v16 row_shr:4 row_mask:0xf bank_mask:0xf
	v_fmac_f32_dpp v23, v23, v17 row_shr:4 row_mask:0xf bank_mask:0xf
	v_mul_f32_dpp v16, v16, v16 row_shr:4 row_mask:0xf bank_mask:0xf
	v_mul_f32_dpp v17, v17, v17 row_shr:4 row_mask:0xf bank_mask:0xf
	v_cndmask_b32_e64 v183, v199, 1.0, vcc
	v_cndmask_b32_e64 v182, v198, 1.0, vcc
	v_fmac_f32_dpp v22, v22, v16 row_shr:8 row_mask:0xf bank_mask:0xf
	v_fmac_f32_dpp v23, v23, v17 row_shr:8 row_mask:0xf bank_mask:0xf
	v_mul_f32_dpp v16, v16, v16 row_shr:8 row_mask:0xf bank_mask:0xf
	v_mul_f32_dpp v17, v17, v17 row_shr:8 row_mask:0xf bank_mask:0xf
	v_and_b32_e32 v181, 0xffff0000, v88
	v_lshlrev_b32_e32 v180, 16, v88
	v_pk_mul_f32 v[20:21], v[20:21], v[182:183]
; #define SCAN_STEP(CTRL, RM) do { _Pragma("unroll") for (int r = 0; r < 16; ++r) { const float ap = DPP_F(1.0f, av[r], CTRL, RM), up = DPP_F(0.0f, uv[r], CTRL, RM); uv[r] = __builtin_fmaf(av[r], up, uv[r]); av[r] = av[r] * ap; } } while (0)
; __device__ __forceinline__ void rec_et(LAS unsigned char* lds, const RecArgs& a, const bf16_t* Wr, const bf16_t* Wi, const int et, const int n, const int r32, const int hi, ...
;     ...
;                     float uu = mult * ig * xcv; if (!valid) { aa = 1.0f; uu = 0.f; }
;                     av[r] = aa; uv[r] = uu; }
;     ...
;                 SCAN_STEP(0x111, 0xf); SCAN_STEP(0x112, 0xf); SCAN_STEP(0x114, 0xf); SCAN_STEP(0x118, 0xf);
;                 SCAN_STEP(0x142, 0xa);
	v_pk_mul_f32 v[20:21], v[20:21], v[180:181]
	v_fmac_f32_dpp v22, v22, v16 row_bcast:15 row_mask:0xa bank_mask:0xf
	v_fmac_f32_dpp v23, v23, v17 row_bcast:15 row_mask:0xa bank_mask:0xf
	v_mul_f32_dpp v16, v16, v16 row_bcast:15 row_mask:0xa bank_mask:0xf
	v_mul_f32_dpp v17, v17, v17 row_bcast:15 row_mask:0xa bank_mask:0xf
	v_mov_b32_e32 v86, v22
	v_mov_b32_e32 v87, v23
	v_mov_b32_e32 v176, v16
	v_mov_b32_e32 v177, v17
	v_cndmask_b32_e64 v17, 1.0, v189, s[38:39]
	v_cndmask_b32_e64 v16, 1.0, v185, s[38:39]
	v_cndmask_b32_e64 v21, 0, v21, s[38:39]
	v_cndmask_b32_e64 v20, 0, v20, s[38:39]
	s_nop 1
	v_fmac_f32_dpp v20, v20, v16 row_shr:1 row_mask:0xf bank_mask:0xf
	v_fmac_f32_dpp v21, v21, v17 row_shr:1 row_mask:0xf bank_mask:0xf
	v_mul_f32_dpp v16, v16, v16 row_shr:1 row_mask:0xf bank_mask:0xf
	v_mul_f32_dpp v17, v17, v17 row_shr:1 row_mask:0xf bank_mask:0xf
	v_fmac_f32_dpp v20, v20, v16 row_shr:2 row_mask:0xf bank_mask:0xf
	v_fmac_f32_dpp v21, v21, v17 row_shr:2 row_mask:0xf bank_mask:0xf
	v_mul_f32_dpp v16, v16, v16 row_shr:2 row_mask:0xf bank_mask:0xf
	v_mul_f32_dpp v17, v17, v17 row_shr:2 row_mask:0xf bank_mask:0xf
	v_fmac_f32_dpp v20, v20, v16 row_shr:4 row_mask:0xf bank_mask:0xf
	v_fmac_f32_dpp v21, v21, v17 row_shr:4 row_mask:0xf bank_mask:0xf
	v_mul_f32_dpp v16, v16, v16 row_shr:4 row_mask:0xf bank_mask:0xf
	v_mul_f32_dpp v17, v17, v17 row_shr:4 row_mask:0xf bank_mask:0xf
	v_fmac_f32_dpp v20, v20, v16 row_shr:8 row_mask:0xf bank_mask:0xf
	v_fmac_f32_dpp v21, v21, v17 row_shr:8 row_mask:0xf bank_mask:0xf
	v_mul_f32_dpp v16, v16, v16 row_shr:8 row_mask:0xf bank_mask:0xf
	v_mul_f32_dpp v17, v17, v17 row_shr:8 row_mask:0xf bank_mask:0xf
	v_fmac_f32_dpp v20, v20, v16 row_bcast:15 row_mask:0xa bank_mask:0xf
	v_fmac_f32_dpp v21, v21, v17 row_bcast:15 row_mask:0xa bank_mask:0xf
	v_mul_f32_dpp v16, v16, v16 row_bcast:15 row_mask:0xa bank_mask:0xf
	v_mul_f32_dpp v17, v17, v17 row_bcast:15 row_mask:0xa bank_mask:0xf
	v_mov_b32_e32 v180, v20
	v_mov_b32_e32 v181, v21
	v_mov_b32_e32 v178, v16
	v_mov_b32_e32 v179, v17
	v_cndmask_b32_e64 v17, 1.0, v200, s[38:39]
	v_cndmask_b32_e64 v16, 1.0, v190, s[38:39]
	v_cndmask_b32_e64 v88, v201, 1.0, vcc
	v_and_b32_e32 v33, 0xffff0000, v89
	v_lshlrev_b32_e32 v32, 16, v89
	v_cndmask_b32_e64 v89, v202, 1.0, vcc
	v_pk_mul_f32 v[18:19], v[18:19], v[88:89]
	v_mul_f32_e32 v2, 0xbfb8aa3b, v2
	v_pk_mul_f32 v[18:19], v[18:19], v[32:33]
	v_cndmask_b32_e64 v19, 0, v19, s[38:39]
	v_cndmask_b32_e64 v18, 0, v18, s[38:39]
	v_exp_f32_e32 v2, v2
	s_nop 1
	v_fmac_f32_dpp v18, v18, v16 row_shr:1 row_mask:0xf bank_mask:0xf
	v_fmac_f32_dpp v19, v19, v17 row_shr:1 row_mask:0xf bank_mask:0xf
	v_mul_f32_dpp v16, v16, v16 row_shr:1 row_mask:0xf bank_mask:0xf
	v_mul_f32_dpp v17, v17, v17 row_shr:1 row_mask:0xf bank_mask:0xf
	v_cndmask_b32_e64 v33, v187, 1.0, vcc
	v_fmac_f32_dpp v18, v18, v16 row_shr:2 row_mask:0xf bank_mask:0xf
	v_fmac_f32_dpp v19, v19, v17 row_shr:2 row_mask:0xf bank_mask:0xf
	v_mul_f32_dpp v16, v16, v16 row_shr:2 row_mask:0xf bank_mask:0xf
	v_mul_f32_dpp v17, v17, v17 row_shr:2 row_mask:0xf bank_mask:0xf
	v_fmac_f32_dpp v18, v18, v16 row_shr:4 row_mask:0xf bank_mask:0xf
	v_fmac_f32_dpp v19, v19, v17 row_shr:4 row_mask:0xf bank_mask:0xf
	v_mul_f32_dpp v16, v16, v16 row_shr:4 row_mask:0xf bank_mask:0xf
	v_mul_f32_dpp v17, v17, v17 row_shr:4 row_mask:0xf bank_mask:0xf
	v_fmac_f32_dpp v18, v18, v16 row_shr:8 row_mask:0xf bank_mask:0xf
	v_fmac_f32_dpp v19, v19, v17 row_shr:8 row_mask:0xf bank_mask:0xf
	v_mul_f32_dpp v16, v16, v16 row_shr:8 row_mask:0xf bank_mask:0xf
	v_mul_f32_dpp v17, v17, v17 row_shr:8 row_mask:0xf bank_mask:0xf
	v_fmac_f32_dpp v18, v18, v16 row_bcast:15 row_mask:0xa bank_mask:0xf
	v_fmac_f32_dpp v19, v19, v17 row_bcast:15 row_mask:0xa bank_mask:0xf
	v_mul_f32_dpp v16, v16, v16 row_bcast:15 row_mask:0xa bank_mask:0xf
	v_mul_f32_dpp v17, v17, v17 row_bcast:15 row_mask:0xa bank_mask:0xf
	v_mov_b32_e32 v88, v18
	v_mov_b32_e32 v89, v19
	v_mov_b32_e32 v182, v16
	v_mov_b32_e32 v183, v17
	v_cndmask_b32_e64 v17, 1.0, v203, s[38:39]
	v_cndmask_b32_e64 v16, 1.0, v184, s[38:39]
	v_cndmask_b32_e64 v32, v186, 1.0, vcc
	v_pk_mul_f32 v[8:9], v[8:9], v[32:33]
	v_add_f32_e32 v2, 1.0, v2
	v_rcp_f32_e32 v5, v2
	s_waitcnt lgkmcnt(0)
	v_and_b32_e32 v31, 0xffff0000, v82
	v_lshlrev_b32_e32 v30, 16, v82
	v_pk_mul_f32 v[8:9], v[8:9], v[30:31]
	v_cndmask_b32_e64 v9, 0, v9, s[38:39]
	v_cndmask_b32_e64 v8, 0, v8, s[38:39]
	v_fma_f32 v2, -v15, v15, 1.0
	s_nop 1
	v_fmac_f32_dpp v8, v8, v16 row_shr:1 row_mask:0xf bank_mask:0xf
	v_fmac_f32_dpp v9, v9, v17 row_shr:1 row_mask:0xf bank_mask:0xf
	v_mul_f32_dpp v16, v16, v16 row_shr:1 row_mask:0xf bank_mask:0xf
	v_mul_f32_dpp v17, v17, v17 row_shr:1 row_mask:0xf bank_mask:0xf
	v_max_f32_e32 v2, 0, v2
	v_fmac_f32_dpp v8, v8, v16 row_shr:2 row_mask:0xf bank_mask:0xf
	v_fmac_f32_dpp v9, v9, v17 row_shr:2 row_mask:0xf bank_mask:0xf
	v_mul_f32_dpp v16, v16, v16 row_shr:2 row_mask:0xf bank_mask:0xf
	v_mul_f32_dpp v17, v17, v17 row_shr:2 row_mask:0xf bank_mask:0xf
	v_fmac_f32_dpp v8, v8, v16 row_shr:4 row_mask:0xf bank_mask:0xf
	v_fmac_f32_dpp v9, v9, v17 row_shr:4 row_mask:0xf bank_mask:0xf
	v_mul_f32_dpp v16, v16, v16 row_shr:4 row_mask:0xf bank_mask:0xf
	v_mul_f32_dpp v17, v17, v17 row_shr:4 row_mask:0xf bank_mask:0xf
	v_fmac_f32_dpp v8, v8, v16 row_shr:8 row_mask:0xf bank_mask:0xf
	v_fmac_f32_dpp v9, v9, v17 row_shr:8 row_mask:0xf bank_mask:0xf
	v_mul_f32_dpp v16, v16, v16 row_shr:8 row_mask:0xf bank_mask:0xf
	v_mul_f32_dpp v17, v17, v17 row_shr:8 row_mask:0xf bank_mask:0xf
	v_fmac_f32_dpp v8, v8, v16 row_bcast:15 row_mask:0xa bank_mask:0xf
	v_fmac_f32_dpp v9, v9, v17 row_bcast:15 row_mask:0xa bank_mask:0xf
; #define LAS __attribute__((address_space(3)))
; __device__ __forceinline__ float bf2f(unsigned short v) { return __uint_as_float((unsigned)v << 16); }
; #define SCAN_STEP(CTRL, RM) do { _Pragma("unroll") for (int r = 0; r < 16; ++r) { const float ap = DPP_F(1.0f, av[r], CTRL, RM), up = DPP_F(0.0f, uv[r], CTRL, RM); uv[r] = __builtin_fmaf(av[r], up, uv[r]); av[r] = av[r] * ap; } } while (0)
; __device__ __forceinline__ void rec_et(LAS unsigned char* lds, const RecArgs& a, const bf16_t* Wr, const bf16_t* Wi, const int et, const int n, const int r32, const int hi, ...
;     ...
;                 for (int r = 0; r < 16; ++r) { const int ch = 64 * n + 32 * et + (r & 3) + 8 * (r >> 2) + 4 * hi;
;                     const float xcv = bf2f(*(const LAS unsigned short*)(lds + tok * XC_STRIDE + ch * 2));
;                     const float rg = __builtin_amdgcn_rcpf(1.0f + __expf(-(accr[r] + Pbrg[ch]))), ig = __builtin_amdgcn_rcpf(1.0f + __expf(-(acci[r] + Pbig[ch])));
;                     const float la = rg * Plsl[ch]; float aa = __expf(la); float mult = __builtin_amdgcn_sqrtf(fmaxf(__builtin_fmaf(-aa, aa, 1.0f), 0.f)); if (t == 0) mult = 1.0f;
;                     float uu = mult * ig * xcv; if (!valid) { aa = 1.0f; uu = 0.f; }
;                     av[r] = aa; uv[r] = uu; }
;     ...
;                 SCAN_STEP(0x111, 0xf); SCAN_STEP(0x112, 0xf); SCAN_STEP(0x114, 0xf); SCAN_STEP(0x118, 0xf);
;                 SCAN_STEP(0x142, 0xa);
	v_mul_f32_dpp v16, v16, v16 row_bcast:15 row_mask:0xa bank_mask:0xf
	v_mul_f32_dpp v17, v17, v17 row_bcast:15 row_mask:0xa bank_mask:0xf
	v_mov_b32_e32 v186, v8
	v_mov_b32_e32 v187, v9
	v_mov_b32_e32 v184, v16
	v_mov_b32_e32 v185, v17
	v_cndmask_b32_e64 v9, 1.0, v29, s[38:39]
	v_cndmask_b32_e64 v8, 1.0, v188, s[38:39]
	v_cndmask_b32_e64 v29, v28, 1.0, vcc
	v_cndmask_b32_e64 v28, v27, 1.0, vcc
	v_pk_mul_f32 v[6:7], v[6:7], v[28:29]
	v_sqrt_f32_e32 v14, v2
	v_and_b32_e32 v25, 0xffff0000, v83
	v_lshlrev_b32_e32 v24, 16, v83
	v_pk_mul_f32 v[6:7], v[6:7], v[24:25]
	v_cndmask_b32_e64 v7, 0, v7, s[38:39]
	v_cndmask_b32_e64 v6, 0, v6, s[38:39]
	v_mul_f32_e32 v0, 0xbfb8aa3b, v0
	s_nop 1
	v_fmac_f32_dpp v6, v6, v8 row_shr:1 row_mask:0xf bank_mask:0xf
	v_fmac_f32_dpp v7, v7, v9 row_shr:1 row_mask:0xf bank_mask:0xf
	v_mul_f32_dpp v8, v8, v8 row_shr:1 row_mask:0xf bank_mask:0xf
	v_mul_f32_dpp v9, v9, v9 row_shr:1 row_mask:0xf bank_mask:0xf
	v_exp_f32_e32 v0, v0
	v_fmac_f32_dpp v6, v6, v8 row_shr:2 row_mask:0xf bank_mask:0xf
	v_fmac_f32_dpp v7, v7, v9 row_shr:2 row_mask:0xf bank_mask:0xf
	v_mul_f32_dpp v8, v8, v8 row_shr:2 row_mask:0xf bank_mask:0xf
	v_mul_f32_dpp v9, v9, v9 row_shr:2 row_mask:0xf bank_mask:0xf
	v_fmac_f32_dpp v6, v6, v8 row_shr:4 row_mask:0xf bank_mask:0xf
	v_fmac_f32_dpp v7, v7, v9 row_shr:4 row_mask:0xf bank_mask:0xf
	v_mul_f32_dpp v8, v8, v8 row_shr:4 row_mask:0xf bank_mask:0xf
	v_mul_f32_dpp v9, v9, v9 row_shr:4 row_mask:0xf bank_mask:0xf
	v_fmac_f32_dpp v6, v6, v8 row_shr:8 row_mask:0xf bank_mask:0xf
	v_fmac_f32_dpp v7, v7, v9 row_shr:8 row_mask:0xf bank_mask:0xf
	v_mul_f32_dpp v8, v8, v8 row_shr:8 row_mask:0xf bank_mask:0xf
	v_mul_f32_dpp v9, v9, v9 row_shr:8 row_mask:0xf bank_mask:0xf
	v_fmac_f32_dpp v6, v6, v8 row_bcast:15 row_mask:0xa bank_mask:0xf
	v_fmac_f32_dpp v7, v7, v9 row_bcast:15 row_mask:0xa bank_mask:0xf
	v_mul_f32_dpp v8, v8, v8 row_bcast:15 row_mask:0xa bank_mask:0xf
	v_mul_f32_dpp v9, v9, v9 row_bcast:15 row_mask:0xa bank_mask:0xf
	v_mov_b32_e32 v82, v6
	v_mov_b32_e32 v83, v7
	v_mov_b32_e32 v188, v8
	v_mov_b32_e32 v189, v9
	v_cndmask_b32_e64 v7, 1.0, v15, s[38:39]
	v_cndmask_b32_e64 v6, 1.0, v26, s[38:39]
	v_cndmask_b32_e64 v15, v14, 1.0, vcc
	v_cndmask_b32_e64 v14, v12, 1.0, vcc
	v_pk_mul_f32 v[4:5], v[4:5], v[14:15]
	v_add_f32_e32 v0, 1.0, v0
	v_and_b32_e32 v23, 0xffff0000, v84
	v_lshlrev_b32_e32 v22, 16, v84
	v_pk_mul_f32 v[4:5], v[4:5], v[22:23]
	v_rcp_f32_e32 v0, v0
	v_cndmask_b32_e64 v5, 0, v5, s[38:39]
	v_cndmask_b32_e64 v4, 0, v4, s[38:39]
	v_mul_f32_e32 v0, v81, v0
	s_nop 1
	v_fmac_f32_dpp v4, v4, v6 row_shr:1 row_mask:0xf bank_mask:0xf
	v_fmac_f32_dpp v5, v5, v7 row_shr:1 row_mask:0xf bank_mask:0xf
	v_mul_f32_dpp v6, v6, v6 row_shr:1 row_mask:0xf bank_mask:0xf
	v_mul_f32_dpp v7, v7, v7 row_shr:1 row_mask:0xf bank_mask:0xf
	v_mul_f32_e32 v0, 0x3fb8aa3b, v0
	v_fmac_f32_dpp v4, v4, v6 row_shr:2 row_mask:0xf bank_mask:0xf
	v_fmac_f32_dpp v5, v5, v7 row_shr:2 row_mask:0xf bank_mask:0xf
	v_mul_f32_dpp v6, v6, v6 row_shr:2 row_mask:0xf bank_mask:0xf
	v_mul_f32_dpp v7, v7, v7 row_shr:2 row_mask:0xf bank_mask:0xf
	v_mul_f32_e32 v3, 0xbfb8aa3b, v3
	v_exp_f32_e32 v13, v0
	v_fmac_f32_dpp v4, v4, v6 row_shr:4 row_mask:0xf bank_mask:0xf
	v_fmac_f32_dpp v5, v5, v7 row_shr:4 row_mask:0xf bank_mask:0xf
	v_mul_f32_dpp v6, v6, v6 row_shr:4 row_mask:0xf bank_mask:0xf
	v_mul_f32_dpp v7, v7, v7 row_shr:4 row_mask:0xf bank_mask:0xf
	v_exp_f32_e32 v3, v3
	v_mul_f32_e32 v10, 0xbfb8aa3b, v10
	v_fmac_f32_dpp v4, v4, v6 row_shr:8 row_mask:0xf bank_mask:0xf
	v_fmac_f32_dpp v5, v5, v7 row_shr:8 row_mask:0xf bank_mask:0xf
	v_mul_f32_dpp v6, v6, v6 row_shr:8 row_mask:0xf bank_mask:0xf
	v_mul_f32_dpp v7, v7, v7 row_shr:8 row_mask:0xf bank_mask:0xf
	v_exp_f32_e32 v10, v10
	v_fmac_f32_dpp v4, v4, v6 row_bcast:15 row_mask:0xa bank_mask:0xf
	v_fmac_f32_dpp v5, v5, v7 row_bcast:15 row_mask:0xa bank_mask:0xf
	v_mul_f32_dpp v6, v6, v6 row_bcast:15 row_mask:0xa bank_mask:0xf
	v_mul_f32_dpp v7, v7, v7 row_bcast:15 row_mask:0xa bank_mask:0xf
	v_mov_b32_e32 v202, v4
	v_mov_b32_e32 v203, v5
	v_mov_b32_e32 v190, v6
	v_mov_b32_e32 v191, v7
	v_cndmask_b32_e64 v5, 1.0, v13, s[38:39]
	v_cndmask_b32_e64 v4, 1.0, v11, s[38:39]
	v_add_f32_e32 v2, 1.0, v3
	v_fma_f32 v3, -v11, v11, 1.0
	v_max_f32_e32 v3, 0, v3
	v_sqrt_f32_e32 v0, v3
	v_add_f32_e32 v3, 1.0, v10
	v_fma_f32 v10, -v13, v13, 1.0
	v_max_f32_e32 v10, 0, v10
	v_sqrt_f32_e32 v10, v10
	v_rcp_f32_e32 v2, v2
	v_rcp_f32_e32 v3, v3
	v_cndmask_b32_e64 v11, v10, 1.0, vcc
	v_cndmask_b32_e64 v10, v0, 1.0, vcc
	v_and_b32_e32 v17, 0xffff0000, v85
	v_lshlrev_b32_e32 v16, 16, v85
	v_pk_mul_f32 v[2:3], v[2:3], v[10:11]
	v_pk_mul_f32 v[2:3], v[2:3], v[16:17]
	v_cndmask_b32_e64 v3, 0, v3, s[38:39]
	v_cndmask_b32_e64 v2, 0, v2, s[38:39]
	s_nop 0
	s_nop 1
	v_fmac_f32_dpp v2, v2, v4 row_shr:1 row_mask:0xf bank_mask:0xf
	v_fmac_f32_dpp v3, v3, v5 row_shr:1 row_mask:0xf bank_mask:0xf
	v_mul_f32_dpp v4, v4, v4 row_shr:1 row_mask:0xf bank_mask:0xf
	v_mul_f32_dpp v5, v5, v5 row_shr:1 row_mask:0xf bank_mask:0xf
	s_nop 0
	v_fmac_f32_dpp v2, v2, v4 row_shr:2 row_mask:0xf bank_mask:0xf
	v_fmac_f32_dpp v3, v3, v5 row_shr:2 row_mask:0xf bank_mask:0xf
	v_mul_f32_dpp v4, v4, v4 row_shr:2 row_mask:0xf bank_mask:0xf
	v_mul_f32_dpp v5, v5, v5 row_shr:2 row_mask:0xf bank_mask:0xf
	s_nop 0
	v_fmac_f32_dpp v2, v2, v4 row_shr:4 row_mask:0xf bank_mask:0xf
	v_fmac_f32_dpp v3, v3, v5 row_shr:4 row_mask:0xf bank_mask:0xf
	v_mul_f32_dpp v4, v4, v4 row_shr:4 row_mask:0xf bank_mask:0xf
	v_mul_f32_dpp v5, v5, v5 row_shr:4 row_mask:0xf bank_mask:0xf
	s_nop 0
	v_fmac_f32_dpp v2, v2, v4 row_shr:8 row_mask:0xf bank_mask:0xf
	v_fmac_f32_dpp v3, v3, v5 row_shr:8 row_mask:0xf bank_mask:0xf
	v_mul_f32_dpp v4, v4, v4 row_shr:8 row_mask:0xf bank_mask:0xf
	v_mul_f32_dpp v5, v5, v5 row_shr:8 row_mask:0xf bank_mask:0xf
	s_nop 0
	v_fmac_f32_dpp v2, v2, v4 row_bcast:15 row_mask:0xa bank_mask:0xf
	v_fmac_f32_dpp v3, v3, v5 row_bcast:15 row_mask:0xa bank_mask:0xf
	v_mul_f32_dpp v4, v4, v4 row_bcast:15 row_mask:0xa bank_mask:0xf
	v_mul_f32_dpp v5, v5, v5 row_bcast:15 row_mask:0xa bank_mask:0xf
	v_mov_b32_e32 v84, v2
	v_mov_b32_e32 v85, v3
	v_mov_b32_e32 v204, v4
	v_mov_b32_e32 v205, v5
	s_cbranch_scc1 .LBB0_490
; __device__ __forceinline__ void rec_et(LAS unsigned char* lds, const RecArgs& a, const bf16_t* Wr, const bf16_t* Wi, const int et, const int n, const int r32, const int hi, ...
;     ...
; #pragma unroll
;                     for (int r = 0; r < 16; ++r) { uv[r] = av[r] * H0[r] + uv[r]; av[r] = av[r] * A0[r]; }
;                 }
	v_pk_fma_f32 v[4:5], v[170:171], v[204:205], v[84:85] op_sel:[1,0,0] op_sel_hi:[0,1,1]
	v_pk_mul_f32 v[8:9], v[168:169], v[204:205] op_sel:[1,0] op_sel_hi:[0,1]
	v_pk_fma_f32 v[26:27], v[142:143], v[172:173], v[174:175] op_sel:[1,0,0] op_sel_hi:[0,1,1]
	v_pk_mul_f32 v[30:31], v[140:141], v[172:173] op_sel:[1,0] op_sel_hi:[0,1]
	v_pk_fma_f32 v[28:29], v[146:147], v[176:177], v[86:87] op_sel:[1,0,0] op_sel_hi:[0,1,1]
	v_pk_mul_f32 v[32:33], v[144:145], v[176:177] op_sel:[1,0] op_sel_hi:[0,1]
	v_pk_fma_f32 v[18:19], v[150:151], v[178:179], v[180:181] op_sel:[1,0,0] op_sel_hi:[0,1,1]
	v_pk_mul_f32 v[22:23], v[148:149], v[178:179] op_sel:[1,0] op_sel_hi:[0,1]
	v_pk_fma_f32 v[20:21], v[154:155], v[182:183], v[88:89] op_sel:[1,0,0] op_sel_hi:[0,1,1]
	v_pk_mul_f32 v[24:25], v[152:153], v[182:183] op_sel:[1,0] op_sel_hi:[0,1]
	v_pk_fma_f32 v[10:11], v[158:159], v[184:185], v[186:187] op_sel:[1,0,0] op_sel_hi:[0,1,1]
	v_pk_mul_f32 v[14:15], v[156:157], v[184:185] op_sel:[1,0] op_sel_hi:[0,1]
	v_pk_fma_f32 v[12:13], v[162:163], v[188:189], v[82:83] op_sel:[1,0,0] op_sel_hi:[0,1,1]
	v_pk_mul_f32 v[16:17], v[160:161], v[188:189] op_sel:[1,0] op_sel_hi:[0,1]
	v_pk_fma_f32 v[2:3], v[166:167], v[190:191], v[202:203] op_sel:[1,0,0] op_sel_hi:[0,1,1]
	v_pk_mul_f32 v[6:7], v[164:165], v[190:191] op_sel:[1,0] op_sel_hi:[0,1]
	v_mov_b64_e32 v[206:207], v[8:9]
	v_mov_b64_e32 v[208:209], v[4:5]
	s_cbranch_execnz .LBB0_486
